# v14 plus next-item queue-pop prefetch issued in the item epilogue
# speedup vs baseline: 1.0334x; 1.0052x over previous
.LBB0_495:
	s_and_b64 vcc, exec, s[20:21]
	s_cbranch_vccnz .LBB0_492
	s_mov_b32 s100, 0
	s_branch .LBB0_500

.Lattn_no_rerun:
	s_cbranch_vccnz .LBB0_494
	s_and_saveexec_b64 s[24:25], s[46:47]
	s_cbranch_execz .Lq_pref_skip1
	v_mov_b32_e32 v140, 1
	global_atomic_add v81, v1, v140, s[18:19] sc0
.Lq_pref_skip1:
	s_or_b64 exec, exec, s[24:25]
	v_add_u32_e32 v8, s33, v80
	ds_read2st64_b32 v[84:85], v8 offset1:1
	ds_read2st64_b32 v[86:87], v8 offset0:2 offset1:3
	ds_read2st64_b32 v[88:89], v8 offset0:4 offset1:5
	ds_read2st64_b32 v[90:91], v8 offset0:6 offset1:7
	ds_read2st64_b32 v[92:93], v8 offset0:8 offset1:9
	ds_read2st64_b32 v[94:95], v8 offset0:10 offset1:11
	ds_read2st64_b32 v[96:97], v8 offset0:12 offset1:13
	ds_read2st64_b32 v[98:99], v8 offset0:14 offset1:15
	ds_read2st64_b32 v[100:101], v8 offset0:16 offset1:17
	ds_read2st64_b32 v[102:103], v8 offset0:18 offset1:19
	ds_read2st64_b32 v[104:105], v8 offset0:20 offset1:21
	ds_read2st64_b32 v[106:107], v8 offset0:22 offset1:23
	ds_read2st64_b32 v[108:109], v8 offset0:24 offset1:25
	ds_read2st64_b32 v[110:111], v8 offset0:26 offset1:27
	ds_read2st64_b32 v[112:113], v8 offset0:28 offset1:29
	ds_read2st64_b32 v[114:115], v8 offset0:30 offset1:31
	ds_read2st64_b32 v[116:117], v8 offset0:32 offset1:33
	ds_read2st64_b32 v[118:119], v8 offset0:34 offset1:35
	ds_read2st64_b32 v[120:121], v8 offset0:36 offset1:37
	ds_read2st64_b32 v[122:123], v8 offset0:38 offset1:39
	ds_read2st64_b32 v[124:125], v8 offset0:40 offset1:41
	ds_read2st64_b32 v[126:127], v8 offset0:42 offset1:43
	ds_read2st64_b32 v[128:129], v8 offset0:44 offset1:45
	ds_read2st64_b32 v[130:131], v8 offset0:46 offset1:47
	ds_read2st64_b32 v[132:133], v8 offset0:48 offset1:49
	ds_read2st64_b32 v[134:135], v8 offset0:50 offset1:51
	ds_read2st64_b32 v[136:137], v8 offset0:52 offset1:53
	ds_read2st64_b32 v[138:139], v8 offset0:54 offset1:55
	ds_read2st64_b32 v[210:211], v8 offset0:56 offset1:57
	ds_read2st64_b32 v[212:213], v8 offset0:58 offset1:59
	ds_read2st64_b32 v[214:215], v8 offset0:60 offset1:61
	ds_read2st64_b32 v[82:83], v8 offset0:62 offset1:63
	v_mov_b32_e32 v5, s14
	v_mov_b32_e32 v4, v64
	v_ashrrev_i32_e32 v225, 31, v224
	v_lshl_add_u64 v[208:209], v[224:225], 2, s[0:1]
	global_load_dwordx4 v[142:145], v[208:209], off
	global_load_dwordx4 v[146:149], v[208:209], off offset:32
	global_load_dwordx4 v[150:153], v[208:209], off offset:64
	global_load_dwordx4 v[154:157], v[208:209], off offset:96
	global_load_dwordx4 v[158:161], v[208:209], off offset:128
	global_load_dwordx4 v[162:165], v[208:209], off offset:160
	global_load_dwordx4 v[166:169], v[208:209], off offset:192
	global_load_dwordx4 v[170:173], v[208:209], off offset:224
	global_load_dwordx4 v[174:177], v[208:209], off offset:256
	global_load_dwordx4 v[178:181], v[208:209], off offset:288
	global_load_dwordx4 v[182:185], v[208:209], off offset:320
	global_load_dwordx4 v[186:189], v[208:209], off offset:352
	global_load_dwordx4 v[190:193], v[208:209], off offset:384
	global_load_dwordx4 v[194:197], v[208:209], off offset:416
	global_load_dwordx4 v[198:201], v[208:209], off offset:448
	global_load_dwordx4 v[202:205], v[208:209], off offset:480
	v_ashrrev_i32_e32 v223, 31, v222
	s_waitcnt lgkmcnt(15)
	v_mov_b32_e32 v3, v84
	v_pk_mul_f32 v[10:11], v[4:5], v[2:3]
	v_mov_b32_e32 v4, v65
	v_mov_b32_e32 v3, v85
	v_pk_mul_f32 v[6:7], v[4:5], v[2:3]
	v_mov_b32_e32 v4, v66
	v_sub_f32_e32 v12, v6, v7
	v_sub_f32_e32 v0, v10, v11
	v_ashrrev_i32_e32 v221, 31, v220
	s_waitcnt lgkmcnt(15)
	v_mov_b32_e32 v3, v86
	v_pk_mul_f32 v[10:11], v[4:5], v[2:3]
	v_mov_b32_e32 v4, v67
	v_mov_b32_e32 v3, v87
	v_pk_mul_f32 v[6:7], v[4:5], v[2:3]
	v_mov_b32_e32 v4, v68
	v_sub_f32_e32 v14, v6, v7
	v_sub_f32_e32 v13, v10, v11
	s_waitcnt lgkmcnt(15)
	v_mov_b32_e32 v3, v88
	v_pk_mul_f32 v[10:11], v[4:5], v[2:3]
	v_mov_b32_e32 v4, v69
	v_mov_b32_e32 v3, v89
	v_pk_mul_f32 v[6:7], v[4:5], v[2:3]
	v_mov_b32_e32 v4, v70
	v_sub_f32_e32 v64, v6, v7
	v_sub_f32_e32 v15, v10, v11
	s_waitcnt lgkmcnt(15)
	v_mov_b32_e32 v3, v90
	v_pk_mul_f32 v[10:11], v[4:5], v[2:3]
	v_mov_b32_e32 v4, v71
	v_mov_b32_e32 v3, v91
	v_pk_mul_f32 v[6:7], v[4:5], v[2:3]
	v_mov_b32_e32 v4, v72
	v_sub_f32_e32 v66, v6, v7
	v_sub_f32_e32 v65, v10, v11
	s_waitcnt lgkmcnt(15)
	v_mov_b32_e32 v3, v92
	v_pk_mul_f32 v[10:11], v[4:5], v[2:3]
	v_mov_b32_e32 v4, v73
	v_mov_b32_e32 v3, v93
	v_pk_mul_f32 v[6:7], v[4:5], v[2:3]
	v_mov_b32_e32 v4, v74
	v_sub_f32_e32 v68, v6, v7
	v_sub_f32_e32 v67, v10, v11
	s_waitcnt lgkmcnt(15)
	v_mov_b32_e32 v3, v94
	v_pk_mul_f32 v[10:11], v[4:5], v[2:3]
	v_mov_b32_e32 v4, v75
	v_mov_b32_e32 v3, v95
	v_pk_mul_f32 v[6:7], v[4:5], v[2:3]
	v_mov_b32_e32 v4, v76
	v_sub_f32_e32 v70, v6, v7
	v_sub_f32_e32 v69, v10, v11
	s_waitcnt lgkmcnt(15)
	v_mov_b32_e32 v3, v96
	v_pk_mul_f32 v[10:11], v[4:5], v[2:3]
	v_mov_b32_e32 v4, v77
	v_mov_b32_e32 v3, v97
	v_pk_mul_f32 v[6:7], v[4:5], v[2:3]
	v_mov_b32_e32 v4, v78
	v_sub_f32_e32 v72, v6, v7
	v_sub_f32_e32 v71, v10, v11
	s_waitcnt lgkmcnt(15)
	v_mov_b32_e32 v3, v98
	v_pk_mul_f32 v[10:11], v[4:5], v[2:3]
	v_mov_b32_e32 v4, v79
	v_mov_b32_e32 v3, v99
	v_pk_mul_f32 v[6:7], v[4:5], v[2:3]
	v_mov_b32_e32 v4, v48
	v_sub_f32_e32 v74, v6, v7
	v_sub_f32_e32 v73, v10, v11
	s_waitcnt lgkmcnt(15)
	v_mov_b32_e32 v3, v100
	v_pk_mul_f32 v[10:11], v[4:5], v[2:3]
	v_mov_b32_e32 v4, v49
	v_mov_b32_e32 v3, v101
	v_pk_mul_f32 v[6:7], v[4:5], v[2:3]
	v_mov_b32_e32 v4, v50
	v_sub_f32_e32 v49, v6, v7
	v_sub_f32_e32 v48, v10, v11
	s_waitcnt lgkmcnt(15)
	v_mov_b32_e32 v3, v102
	v_pk_mul_f32 v[10:11], v[4:5], v[2:3]
	v_mov_b32_e32 v4, v51
	v_mov_b32_e32 v3, v103
	v_pk_mul_f32 v[6:7], v[4:5], v[2:3]
	v_mov_b32_e32 v4, v52
	v_sub_f32_e32 v51, v6, v7
	v_sub_f32_e32 v50, v10, v11
	s_waitcnt lgkmcnt(15)
	v_mov_b32_e32 v3, v104
	v_pk_mul_f32 v[10:11], v[4:5], v[2:3]
	v_mov_b32_e32 v4, v53
	v_mov_b32_e32 v3, v105
	v_pk_mul_f32 v[6:7], v[4:5], v[2:3]
	v_mov_b32_e32 v4, v54
	v_sub_f32_e32 v52, v6, v7
	v_sub_f32_e32 v75, v10, v11
	s_waitcnt lgkmcnt(15)
	v_mov_b32_e32 v3, v106
	v_pk_mul_f32 v[10:11], v[4:5], v[2:3]
	v_mov_b32_e32 v4, v55
	v_mov_b32_e32 v3, v107
	v_pk_mul_f32 v[6:7], v[4:5], v[2:3]
	v_mov_b32_e32 v4, v56
	v_sub_f32_e32 v55, v6, v7
	v_sub_f32_e32 v76, v10, v11
	s_waitcnt lgkmcnt(15)
	v_mov_b32_e32 v3, v108
	v_pk_mul_f32 v[10:11], v[4:5], v[2:3]
	v_mov_b32_e32 v4, v57
	v_mov_b32_e32 v3, v109
	v_pk_mul_f32 v[6:7], v[4:5], v[2:3]
	v_mov_b32_e32 v4, v58
	v_sub_f32_e32 v53, v6, v7
	v_sub_f32_e32 v54, v10, v11
	s_waitcnt lgkmcnt(15)
	v_mov_b32_e32 v3, v110
	v_pk_mul_f32 v[10:11], v[4:5], v[2:3]
	v_mov_b32_e32 v4, v59
	v_mov_b32_e32 v3, v111
	v_pk_mul_f32 v[6:7], v[4:5], v[2:3]
	v_mov_b32_e32 v4, v60
	v_sub_f32_e32 v56, v6, v7
	v_sub_f32_e32 v57, v10, v11
	s_waitcnt lgkmcnt(15)
	v_mov_b32_e32 v3, v112
	v_pk_mul_f32 v[10:11], v[4:5], v[2:3]
	v_mov_b32_e32 v4, v61
	v_mov_b32_e32 v3, v113
	v_pk_mul_f32 v[6:7], v[4:5], v[2:3]
	v_mov_b32_e32 v4, v62
	v_sub_f32_e32 v58, v6, v7
	v_sub_f32_e32 v59, v10, v11
	s_waitcnt lgkmcnt(15)
	v_mov_b32_e32 v3, v114
	v_pk_mul_f32 v[10:11], v[4:5], v[2:3]
	v_mov_b32_e32 v4, v63
	v_mov_b32_e32 v3, v115
	v_pk_mul_f32 v[6:7], v[4:5], v[2:3]
	v_mov_b32_e32 v4, v32
	v_sub_f32_e32 v60, v6, v7
	v_sub_f32_e32 v62, v10, v11
	s_waitcnt lgkmcnt(15)
	v_mov_b32_e32 v3, v116
	v_pk_mul_f32 v[10:11], v[4:5], v[2:3]
	v_mov_b32_e32 v4, v33
	v_mov_b32_e32 v3, v117
	v_pk_mul_f32 v[6:7], v[4:5], v[2:3]
	v_mov_b32_e32 v4, v34
	v_sub_f32_e32 v32, v6, v7
	v_sub_f32_e32 v61, v10, v11
	s_waitcnt lgkmcnt(14)
	v_mov_b32_e32 v3, v118
	v_pk_mul_f32 v[10:11], v[4:5], v[2:3]
	v_mov_b32_e32 v4, v35
	v_mov_b32_e32 v3, v119
	v_pk_mul_f32 v[6:7], v[4:5], v[2:3]
	v_mov_b32_e32 v4, v36
	v_sub_f32_e32 v33, v6, v7
	v_sub_f32_e32 v34, v10, v11
	s_waitcnt lgkmcnt(13)
	v_mov_b32_e32 v3, v120
	v_pk_mul_f32 v[10:11], v[4:5], v[2:3]
	v_mov_b32_e32 v4, v37
	v_mov_b32_e32 v3, v121
	v_pk_mul_f32 v[6:7], v[4:5], v[2:3]
	v_mov_b32_e32 v4, v38
	v_sub_f32_e32 v35, v6, v7
	v_sub_f32_e32 v36, v10, v11
	s_waitcnt lgkmcnt(12)
	v_mov_b32_e32 v3, v122
	v_pk_mul_f32 v[10:11], v[4:5], v[2:3]
	v_mov_b32_e32 v4, v39
	v_mov_b32_e32 v3, v123
	v_pk_mul_f32 v[6:7], v[4:5], v[2:3]
	v_mov_b32_e32 v4, v40
	v_sub_f32_e32 v39, v6, v7
	v_sub_f32_e32 v63, v10, v11
	s_waitcnt lgkmcnt(11)
	v_mov_b32_e32 v3, v124
	v_pk_mul_f32 v[10:11], v[4:5], v[2:3]
	v_mov_b32_e32 v4, v41
	v_mov_b32_e32 v3, v125
	v_pk_mul_f32 v[6:7], v[4:5], v[2:3]
	v_mov_b32_e32 v4, v42
	v_sub_f32_e32 v37, v6, v7
	v_sub_f32_e32 v38, v10, v11
	s_waitcnt lgkmcnt(10)
	v_mov_b32_e32 v3, v126
	v_pk_mul_f32 v[10:11], v[4:5], v[2:3]
	v_mov_b32_e32 v4, v43
	v_mov_b32_e32 v3, v127
	v_pk_mul_f32 v[6:7], v[4:5], v[2:3]
	v_mov_b32_e32 v4, v44
	v_sub_f32_e32 v40, v6, v7
	v_sub_f32_e32 v41, v10, v11
	s_waitcnt lgkmcnt(9)
	v_mov_b32_e32 v3, v128
	v_pk_mul_f32 v[10:11], v[4:5], v[2:3]
	v_mov_b32_e32 v4, v45
	v_mov_b32_e32 v3, v129
	v_pk_mul_f32 v[6:7], v[4:5], v[2:3]
	v_mov_b32_e32 v4, v46
	v_sub_f32_e32 v42, v6, v7
	v_sub_f32_e32 v43, v10, v11
	s_waitcnt lgkmcnt(8)
	v_mov_b32_e32 v3, v130
	v_pk_mul_f32 v[10:11], v[4:5], v[2:3]
	v_mov_b32_e32 v4, v47
	v_mov_b32_e32 v3, v131
	v_pk_mul_f32 v[6:7], v[4:5], v[2:3]
	v_mov_b32_e32 v4, v16
	v_sub_f32_e32 v45, v6, v7
	v_sub_f32_e32 v46, v10, v11
	s_waitcnt lgkmcnt(7)
	v_mov_b32_e32 v3, v132
	v_pk_mul_f32 v[10:11], v[4:5], v[2:3]
	v_mov_b32_e32 v4, v17
	v_mov_b32_e32 v3, v133
	v_pk_mul_f32 v[6:7], v[4:5], v[2:3]
	v_mov_b32_e32 v4, v18
	v_sub_f32_e32 v16, v6, v7
	v_sub_f32_e32 v44, v10, v11
	s_waitcnt lgkmcnt(6)
	v_mov_b32_e32 v3, v134
	v_pk_mul_f32 v[10:11], v[4:5], v[2:3]
	v_mov_b32_e32 v4, v19
	v_mov_b32_e32 v3, v135
	v_pk_mul_f32 v[6:7], v[4:5], v[2:3]
	v_mov_b32_e32 v4, v20
	v_sub_f32_e32 v17, v6, v7
	v_sub_f32_e32 v18, v10, v11
	s_waitcnt lgkmcnt(5)
	v_mov_b32_e32 v3, v136
	v_pk_mul_f32 v[10:11], v[4:5], v[2:3]
	v_mov_b32_e32 v4, v21
	v_mov_b32_e32 v3, v137
	v_pk_mul_f32 v[6:7], v[4:5], v[2:3]
	v_mov_b32_e32 v4, v22
	v_sub_f32_e32 v19, v6, v7
	v_sub_f32_e32 v20, v10, v11
	s_waitcnt lgkmcnt(4)
	v_mov_b32_e32 v3, v138
	v_pk_mul_f32 v[10:11], v[4:5], v[2:3]
	v_mov_b32_e32 v4, v23
	v_mov_b32_e32 v3, v139
	v_pk_mul_f32 v[6:7], v[4:5], v[2:3]
	v_mov_b32_e32 v4, v24
	v_sub_f32_e32 v23, v6, v7
	v_sub_f32_e32 v47, v10, v11
	s_waitcnt lgkmcnt(3)
	v_mov_b32_e32 v3, v210
	v_pk_mul_f32 v[10:11], v[4:5], v[2:3]
	v_mov_b32_e32 v4, v25
	v_mov_b32_e32 v3, v211
	v_pk_mul_f32 v[6:7], v[4:5], v[2:3]
	v_mov_b32_e32 v4, v26
	v_sub_f32_e32 v21, v6, v7
	v_sub_f32_e32 v22, v10, v11
	s_waitcnt lgkmcnt(2)
	v_mov_b32_e32 v3, v212
	v_pk_mul_f32 v[10:11], v[4:5], v[2:3]
	v_mov_b32_e32 v4, v27
	v_sub_f32_e32 v25, v10, v11
	v_mul_f32_e32 v10, v0, v0
	v_fmac_f32_e32 v10, v12, v12
	v_fmac_f32_e32 v10, v13, v13
	v_fmac_f32_e32 v10, v14, v14
	v_fmac_f32_e32 v10, v15, v15
	v_fmac_f32_e32 v10, v64, v64
	v_fmac_f32_e32 v10, v65, v65
	v_fmac_f32_e32 v10, v66, v66
	v_fmac_f32_e32 v10, v67, v67
	v_fmac_f32_e32 v10, v68, v68
	v_fmac_f32_e32 v10, v69, v69
	v_fmac_f32_e32 v10, v70, v70
	v_fmac_f32_e32 v10, v71, v71
	v_fmac_f32_e32 v10, v72, v72
	v_fmac_f32_e32 v10, v73, v73
	v_fmac_f32_e32 v10, v74, v74
	v_fmac_f32_e32 v10, v48, v48
	v_fmac_f32_e32 v10, v49, v49
	v_fmac_f32_e32 v10, v50, v50
	v_fmac_f32_e32 v10, v51, v51
	v_fmac_f32_e32 v10, v75, v75
	v_fmac_f32_e32 v10, v52, v52
	v_fmac_f32_e32 v10, v76, v76
	v_fmac_f32_e32 v10, v55, v55
	v_fmac_f32_e32 v10, v54, v54
	v_fmac_f32_e32 v10, v53, v53
	v_fmac_f32_e32 v10, v57, v57
	v_fmac_f32_e32 v10, v56, v56
	v_fmac_f32_e32 v10, v59, v59
	v_fmac_f32_e32 v10, v58, v58
	v_fmac_f32_e32 v10, v62, v62
	v_fmac_f32_e32 v10, v60, v60
	v_fmac_f32_e32 v10, v61, v61
	v_fmac_f32_e32 v10, v32, v32
	v_fmac_f32_e32 v10, v34, v34
	v_fmac_f32_e32 v10, v33, v33
	v_fmac_f32_e32 v10, v36, v36
	v_fmac_f32_e32 v10, v35, v35
	v_fmac_f32_e32 v10, v63, v63
	v_fmac_f32_e32 v10, v39, v39
	v_fmac_f32_e32 v10, v38, v38
	v_fmac_f32_e32 v10, v37, v37
	v_fmac_f32_e32 v10, v41, v41
	v_fmac_f32_e32 v10, v40, v40
	v_fmac_f32_e32 v10, v43, v43
	v_fmac_f32_e32 v10, v42, v42
	v_fmac_f32_e32 v10, v46, v46
	v_fmac_f32_e32 v10, v45, v45
	v_fmac_f32_e32 v10, v44, v44
	v_fmac_f32_e32 v10, v16, v16
	v_mov_b32_e32 v3, v213
	v_fmac_f32_e32 v10, v18, v18
	v_pk_mul_f32 v[4:5], v[4:5], v[2:3]
	v_fmac_f32_e32 v10, v17, v17
	v_sub_f32_e32 v24, v4, v5
	v_fmac_f32_e32 v10, v20, v20
	v_fmac_f32_e32 v10, v19, v19
	v_fmac_f32_e32 v10, v47, v47
	v_fmac_f32_e32 v10, v23, v23
	v_fmac_f32_e32 v10, v22, v22
	s_waitcnt lgkmcnt(1)
	v_pk_mul_f32 v[4:5], s[14:15], v[214:215]
	v_fmac_f32_e32 v10, v21, v21
	v_pk_fma_f32 v[6:7], v[28:29], v[2:3], v[4:5] op_sel_hi:[1,0,1] neg_lo:[0,0,1] neg_hi:[0,0,1]
	v_fmac_f32_e32 v10, v25, v25
	v_pk_mul_f32 v[4:5], v[6:7], v[6:7]
	s_waitcnt lgkmcnt(0)
	v_pk_mul_f32 v[8:9], s[14:15], v[82:83]
	v_fmac_f32_e32 v10, v24, v24
	v_pk_fma_f32 v[8:9], v[30:31], v[2:3], v[8:9] op_sel_hi:[1,0,1] neg_lo:[0,0,1] neg_hi:[0,0,1]
	v_add_f32_e32 v4, v10, v4
	v_pk_mul_f32 v[2:3], v[8:9], v[8:9]
	v_add_f32_e32 v4, v4, v5
	v_add_f32_e32 v2, v4, v2
	v_add_f32_e32 v2, v2, v3
	ds_bpermute_b32 v3, v219, v2
	v_ashrrev_i32_e32 v219, 31, v218
	s_waitcnt lgkmcnt(0)
	v_add_f32_e32 v2, v2, v3
	v_fmamk_f32 v2, v2, 0x3c000000, v207
	v_cmp_gt_f32_e32 vcc, s82, v2
	v_mul_f32_e32 v3, 0x4f800000, v2
	s_nop 0
	v_cndmask_b32_e32 v2, v2, v3, vcc
	v_sqrt_f32_e32 v3, v2
	s_nop 0
	v_add_u32_e32 v4, -1, v3
	v_fma_f32 v5, -v4, v3, v2
	v_cmp_ge_f32_e64 s[48:49], 0, v5
	v_add_u32_e32 v5, 1, v3
	s_nop 0
	v_cndmask_b32_e64 v4, v3, v4, s[48:49]
	v_fma_f32 v3, -v5, v3, v2
	v_cmp_lt_f32_e64 s[48:49], 0, v3
	s_nop 1
	v_cndmask_b32_e64 v3, v4, v5, s[48:49]
	v_mul_f32_e32 v4, 0x37800000, v3
	v_cndmask_b32_e32 v3, v3, v4, vcc
	v_cmp_class_f32_e32 vcc, v2, v227
	s_nop 1
	v_cndmask_b32_e32 v2, v3, v2, vcc
	v_div_scale_f32 v3, s[20:21], v2, v2, v141
	v_rcp_f32_e32 v4, v3
	s_nop 0
	v_fma_f32 v5, -v3, v4, 1.0
	v_fmac_f32_e32 v4, v5, v4
	v_div_scale_f32 v5, vcc, v141, v2, v141
	v_mul_f32_e32 v10, v5, v4
	v_fma_f32 v11, -v3, v10, v5
	v_fmac_f32_e32 v10, v11, v4
	v_fma_f32 v3, -v3, v10, v5
	v_div_fmas_f32 v3, v3, v4, v10
	v_div_fixup_f32 v26, v3, v2, v141
	v_mul_f32_e32 v0, v0, v26
	s_waitcnt vmcnt(0)
	s_and_saveexec_b64 s[24:25], s[46:47]
	s_cbranch_execz .Lq_pref_skip2
	v_mov_b32_e32 v140, s85
	ds_write_b32 v140, v81
.Lq_pref_skip2:
	s_or_b64 exec, exec, s[24:25]
	v_mul_f32_e32 v0, v142, v0
	v_mul_f32_e32 v2, v12, v26
	v_mul_f32_e32 v2, v143, v2
	v_cvt_pk_bf16_f32 v12, v0, v2
	v_mul_f32_e32 v2, v14, v26
	v_mul_f32_e32 v0, v13, v26
	v_mul_f32_e32 v2, v145, v2
	v_mul_f32_e32 v0, v144, v0
	v_cvt_pk_bf16_f32 v13, v0, v2
	v_lshl_add_u64 v[2:3], v[224:225], 1, v[216:217]
	global_store_dwordx2 v[2:3], v[12:13], off
	v_mul_f32_e32 v0, v15, v26
	v_mul_f32_e32 v4, v64, v26
	v_mul_f32_e32 v5, v66, v26
	v_lshl_add_u64 v[12:13], v[222:223], 1, v[216:217]
	v_mul_f32_e32 v0, v146, v0
	v_mul_f32_e32 v4, v147, v4
	v_cvt_pk_bf16_f32 v4, v0, v4
	v_mul_f32_e32 v0, v65, v26
	v_mul_f32_e32 v5, v149, v5
	v_mul_f32_e32 v0, v148, v0
	v_cvt_pk_bf16_f32 v5, v0, v5
	global_store_dwordx2 v[12:13], v[4:5], off
	v_mul_f32_e32 v0, v67, v26
	v_mul_f32_e32 v4, v68, v26
	v_mul_f32_e32 v5, v70, v26
	v_mul_f32_e32 v0, v0, v150
	v_mul_f32_e32 v4, v4, v151
	v_cvt_pk_bf16_f32 v4, v0, v4
	v_mul_f32_e32 v0, v69, v26
	v_mul_f32_e32 v5, v5, v153
	v_mul_f32_e32 v0, v0, v152
	v_cvt_pk_bf16_f32 v5, v0, v5
	v_lshl_add_u64 v[12:13], v[220:221], 1, v[216:217]
	global_store_dwordx2 v[12:13], v[4:5], off
	v_mul_f32_e32 v0, v71, v26
	v_mul_f32_e32 v4, v72, v26
	v_mul_f32_e32 v5, v74, v26
	v_mul_f32_e32 v0, v0, v154
	v_mul_f32_e32 v4, v4, v155
	v_cvt_pk_bf16_f32 v4, v0, v4
	v_mul_f32_e32 v0, v73, v26
	v_mul_f32_e32 v5, v5, v157
	v_lshl_add_u64 v[12:13], v[218:219], 1, v[216:217]
	v_mul_f32_e32 v0, v0, v156
	v_cvt_pk_bf16_f32 v5, v0, v5
	global_store_dwordx2 v[12:13], v[4:5], off
	v_mul_f32_e32 v0, v48, v26
	v_mul_f32_e32 v4, v49, v26
	v_mul_f32_e32 v5, v51, v26
	v_mul_f32_e32 v0, v0, v158
	v_mul_f32_e32 v4, v4, v159
	v_cvt_pk_bf16_f32 v4, v0, v4
	v_mul_f32_e32 v0, v50, v26
	v_mul_f32_e32 v5, v5, v161
	v_mul_f32_e32 v0, v0, v160
	v_cvt_pk_bf16_f32 v5, v0, v5
	global_store_dwordx2 v[2:3], v[4:5], off offset:64
	v_mul_f32_e32 v0, v75, v26
	v_mul_f32_e32 v4, v52, v26
	v_mul_f32_e32 v5, v55, v26
	v_mul_f32_e32 v0, v0, v162
	v_mul_f32_e32 v4, v4, v163
	v_cvt_pk_bf16_f32 v4, v0, v4
	v_mul_f32_e32 v0, v76, v26
	v_mul_f32_e32 v5, v5, v165
	v_mul_f32_e32 v0, v0, v164
	v_cvt_pk_bf16_f32 v5, v0, v5
	global_store_dwordx2 v[2:3], v[4:5], off offset:80
	v_mul_f32_e32 v0, v54, v26
	v_mul_f32_e32 v4, v53, v26
	v_mul_f32_e32 v5, v56, v26
	v_mul_f32_e32 v0, v0, v166
	v_mul_f32_e32 v4, v4, v167
	v_cvt_pk_bf16_f32 v4, v0, v4
	v_mul_f32_e32 v0, v57, v26
	v_mul_f32_e32 v5, v5, v169
	v_mul_f32_e32 v0, v0, v168
	v_cvt_pk_bf16_f32 v5, v0, v5
	global_store_dwordx2 v[2:3], v[4:5], off offset:96
	v_mul_f32_e32 v0, v59, v26
	v_mul_f32_e32 v4, v58, v26
	v_mul_f32_e32 v5, v60, v26
	v_mul_f32_e32 v0, v0, v170
	v_mul_f32_e32 v4, v4, v171
	v_cvt_pk_bf16_f32 v4, v0, v4
	v_mul_f32_e32 v0, v62, v26
	v_mul_f32_e32 v5, v5, v173
	v_mul_f32_e32 v0, v0, v172
	v_cvt_pk_bf16_f32 v5, v0, v5
	global_store_dwordx2 v[2:3], v[4:5], off offset:112
	v_mul_f32_e32 v0, v61, v26
	v_mul_f32_e32 v4, v32, v26
	v_mul_f32_e32 v5, v33, v26
	v_mul_f32_e32 v0, v0, v174
	v_mul_f32_e32 v4, v4, v175
	v_cvt_pk_bf16_f32 v4, v0, v4
	v_mul_f32_e32 v0, v34, v26
	v_mul_f32_e32 v5, v5, v177
	v_mul_f32_e32 v0, v0, v176
	v_cvt_pk_bf16_f32 v5, v0, v5
	global_store_dwordx2 v[2:3], v[4:5], off offset:128
	v_mul_f32_e32 v0, v36, v26
	v_mul_f32_e32 v4, v35, v26
	v_mul_f32_e32 v5, v39, v26
	v_mul_f32_e32 v0, v0, v178
	v_mul_f32_e32 v4, v4, v179
	v_cvt_pk_bf16_f32 v4, v0, v4
	v_mul_f32_e32 v0, v63, v26
	v_mul_f32_e32 v5, v5, v181
	v_mul_f32_e32 v0, v0, v180
	v_cvt_pk_bf16_f32 v5, v0, v5
	global_store_dwordx2 v[2:3], v[4:5], off offset:144
	v_mul_f32_e32 v0, v38, v26
	v_mul_f32_e32 v4, v37, v26
	v_mul_f32_e32 v5, v40, v26
	v_mul_f32_e32 v0, v0, v182
	v_mul_f32_e32 v4, v4, v183
	v_cvt_pk_bf16_f32 v4, v0, v4
	v_mul_f32_e32 v0, v41, v26
	v_mul_f32_e32 v5, v5, v185
	v_mul_f32_e32 v0, v0, v184
	v_cvt_pk_bf16_f32 v5, v0, v5
	global_store_dwordx2 v[2:3], v[4:5], off offset:160
	v_mul_f32_e32 v0, v43, v26
	v_mul_f32_e32 v4, v42, v26
	v_mul_f32_e32 v5, v45, v26
	v_mul_f32_e32 v0, v0, v186
	v_mul_f32_e32 v4, v4, v187
	v_cvt_pk_bf16_f32 v4, v0, v4
	v_mul_f32_e32 v0, v46, v26
	v_mul_f32_e32 v5, v5, v189
	v_mul_f32_e32 v0, v0, v188
	v_cvt_pk_bf16_f32 v5, v0, v5
	global_store_dwordx2 v[2:3], v[4:5], off offset:176
	v_mul_f32_e32 v0, v44, v26
	v_mul_f32_e32 v4, v16, v26
	v_mul_f32_e32 v5, v17, v26
	v_mul_f32_e32 v0, v0, v190
	v_mul_f32_e32 v4, v4, v191
	v_cvt_pk_bf16_f32 v4, v0, v4
	v_mul_f32_e32 v0, v18, v26
	v_mul_f32_e32 v5, v5, v193
	v_mul_f32_e32 v0, v0, v192
	v_cvt_pk_bf16_f32 v5, v0, v5
	global_store_dwordx2 v[2:3], v[4:5], off offset:192
	v_mul_f32_e32 v0, v20, v26
	v_mul_f32_e32 v4, v19, v26
	v_mul_f32_e32 v5, v23, v26
	v_mul_f32_e32 v0, v0, v194
	v_mul_f32_e32 v4, v4, v195
	v_cvt_pk_bf16_f32 v4, v0, v4
	v_mul_f32_e32 v0, v47, v26
	v_mul_f32_e32 v5, v5, v197
	v_mul_f32_e32 v0, v0, v196
	v_cvt_pk_bf16_f32 v5, v0, v5
	global_store_dwordx2 v[2:3], v[4:5], off offset:208
	v_mul_f32_e32 v0, v22, v26
	v_mul_f32_e32 v4, v21, v26
	v_mul_f32_e32 v5, v24, v26
	v_mul_f32_e32 v0, v0, v198
	v_mul_f32_e32 v4, v4, v199
	v_cvt_pk_bf16_f32 v4, v0, v4
	v_mul_f32_e32 v0, v25, v26
	v_mul_f32_e32 v5, v5, v201
	v_mul_f32_e32 v0, v0, v200
	v_cvt_pk_bf16_f32 v5, v0, v5
	global_store_dwordx2 v[2:3], v[4:5], off offset:224
	v_mul_f32_e32 v0, v6, v26
	v_mul_f32_e32 v4, v7, v26
	v_mul_f32_e32 v5, v9, v26
	v_mul_f32_e32 v0, v0, v202
	v_mul_f32_e32 v4, v4, v203
	v_cvt_pk_bf16_f32 v4, v0, v4
	v_mul_f32_e32 v0, v8, v26
	v_mul_f32_e32 v5, v5, v205
	v_mul_f32_e32 v0, v0, v204
	v_cvt_pk_bf16_f32 v5, v0, v5
	global_store_dwordx2 v[2:3], v[4:5], off offset:240
	s_branch .LBB0_494
